# phase3: static priority raise now really conditional on waves 4-7 (compiler had dropped the skip branch so all waves were raised)
# speedup vs baseline: 1.0037x; 1.0032x over previous
.LBB0_717:
	s_cmp_lt_i32 s22, 4
	s_cselect_b64 s[0:1], -1, 0
	s_cmp_gt_i32 s23, 3
	s_cselect_b64 s[2:3], -1, 0
	s_and_b64 s[0:1], s[0:1], s[2:3]
	s_andn2_b64 vcc, exec, s[0:1]
	s_cbranch_vccnz .LBB0_952
	s_movk_i32 s0, 0xff
	v_cmp_lt_u32_e32 vcc, s0, v208
	s_and_saveexec_b64 s[0:1], vcc
	s_cbranch_execz .Lp3_noprio
	s_setprio 1
.Lp3_noprio:
	s_or_b64 exec, exec, s[0:1]
	s_cmpk_eq_i32 s82, 0x100
	s_cselect_b64 s[0:1], -1, 0
	v_writelane_b32 v247, s0, 41
	s_movk_i32 s2, 0x800
	v_and_b32_e32 v1, 7, v208
	v_writelane_b32 v247, s1, 42
	s_and_b64 s[0:1], s[0:1], exec
	s_cselect_b32 s88, s2, 0x810
	s_cmp_ge_i32 s96, s88
	s_cbranch_scc1 .LBB0_856
	v_and_b32_e32 v15, 31, v208
	v_bfe_u32 v3, v208, 5, 1
	s_movk_i32 s0, 0x80
	v_min_u32_e32 v141, 15, v15
	v_cmp_gt_u32_e32 vcc, s0, v208
	s_movk_i32 s0, 0x100
	v_lshlrev_b32_e32 v212, 2, v3
	v_lshlrev_b32_e32 v14, 3, v3
	v_lshrrev_b32_e32 v147, 3, v208
	v_cmp_gt_u32_e64 s[2:3], s0, v208
	s_movk_i32 s0, 0xd0
	v_lshrrev_b32_e32 v12, 2, v208
	v_cmp_eq_u32_e64 s[6:7], 0, v3
	v_lshlrev_b32_e32 v144, 4, v3
	v_sub_u32_e32 v3, v141, v212
	v_mad_u32_u24 v199, v147, s0, 0
	v_mad_u32_u24 v201, v12, s0, 0
	v_mad_u32_u24 v213, v15, s0, 0
	v_cmp_gt_i32_e64 s[0:1], 0, v3
	v_min_u32_e32 v8, 16, v15
	v_mul_u32_u24_e32 v16, 0x600, v141
	v_writelane_b32 v247, s0, 22
	v_mov_b32_e32 v17, 0
	v_lshlrev_b32_e32 v2, 9, v147
	v_writelane_b32 v247, s1, 23
	v_cmp_gt_i32_e64 s[0:1], 1, v3
	v_mov_b32_e32 v4, 0x1e00
	v_cndmask_b32_e32 v10, v4, v2, vcc
	v_writelane_b32 v247, s0, 24
	v_min_u32_e32 v2, 63, v208
	v_mov_b32_e32 v145, v17
	v_writelane_b32 v247, s1, 25
	v_cmp_gt_i32_e64 s[0:1], 2, v3
	v_lshrrev_b32_e32 v2, 2, v2
	v_mul_u32_u24_e32 v11, 0xc00, v2
	v_writelane_b32 v247, s0, 26
	v_lshlrev_b32_e32 v2, 3, v208
	v_lshlrev_b32_e32 v142, 4, v1
	v_writelane_b32 v247, s1, 27
	v_cmp_gt_i32_e64 s[0:1], 3, v3
	v_mov_b32_e32 v143, v17
	v_and_b32_e32 v2, 24, v2
	v_writelane_b32 v247, s0, 28
	v_lshlrev_b32_e32 v4, 4, v208
	v_and_b32_e32 v202, 48, v4
	v_writelane_b32 v247, s1, 29
	v_cmp_gt_i32_e64 s[0:1], 8, v3
	v_lshlrev_b32_e32 v4, 6, v147
	v_sub_u32_e32 v204, v199, v4
	v_writelane_b32 v247, s0, 16
	v_mul_u32_u24_e32 v4, 0x1800, v141
	v_mov_b32_e32 v5, v17
	v_writelane_b32 v247, s1, 17
	v_cmp_gt_i32_e64 s[0:1], 9, v3
	v_mul_u32_u24_e32 v6, 0x1800, v147
	v_mov_b32_e32 v7, 0x16800
	v_writelane_b32 v247, s0, 43
	v_cndmask_b32_e32 v6, v7, v6, vcc
	v_mov_b32_e32 v7, v17
	v_writelane_b32 v247, s1, 44
	v_cmp_gt_i32_e64 s[0:1], 10, v3
	v_mul_u32_u24_e32 v150, 0x1800, v12
	v_lshlrev_b32_e32 v148, 10, v147
	v_writelane_b32 v247, s0, 45
	v_lshlrev_b32_e32 v140, 3, v1
	s_movk_i32 s8, 0x90
	v_writelane_b32 v247, s1, 46
	v_cmp_gt_i32_e64 s[0:1], 11, v3
	v_and_b32_e32 v3, 63, v208
	v_cmp_gt_u32_e64 s[26:27], 32, v3
	v_writelane_b32 v247, s0, 47
	v_cmp_eq_u32_e64 s[28:29], 0, v3
	v_sub_u32_e32 v3, v8, v212
	v_writelane_b32 v247, s1, 48
	v_cmp_lt_u32_e64 s[0:1], 15, v15
	v_lshl_add_u64 v[8:9], s[20:21], 0, v[16:17]
	v_lshl_add_u64 v[8:9], v[8:9], 0, v[144:145]
	v_writelane_b32 v247, s0, 18
	v_lshlrev_b32_e32 v16, 1, v10
	v_and_b32_e32 v205, 0x60, v142
	v_writelane_b32 v247, s1, 19
	v_cmp_lt_i32_e64 s[0:1], 0, v3
	v_cmp_gt_u32_e64 s[4:5], 2, v1
	v_mul_u32_u24_e32 v198, 0xd0, v147
	v_writelane_b32 v247, s0, 49
	s_mov_b32 s9, 0
	v_mul_u32_u24_e32 v200, 0xd0, v12
	v_writelane_b32 v247, s1, 50
	v_cmp_lt_i32_e64 s[0:1], 1, v3
	v_mul_u32_u24_e32 v203, 0x90, v147
	v_add_u32_e32 v206, v204, v205
	v_writelane_b32 v247, s0, 51
	v_and_b32_e32 v207, 8, v140
	v_mul_u32_u24_e32 v210, 0x90, v15
	v_writelane_b32 v247, s1, 52
	v_cmp_lt_i32_e64 s[0:1], 2, v3
	v_mul_u32_u24_e32 v211, 0xd0, v15
	v_add_u32_e32 v214, 0, v144
	v_writelane_b32 v247, s0, 53
	s_movk_i32 s45, 0x1800
	v_lshlrev_b32_e32 v146, 15, v147
	v_writelane_b32 v247, s1, 54
	v_cmp_lt_i32_e64 s[0:1], 3, v3
	v_add_u32_e32 v215, 1, v15
	v_not_b32_e32 v216, v212
	v_writelane_b32 v247, s0, 55
	v_mov_b32_e32 v149, v17
	s_waitcnt lgkmcnt(0)
	v_mov_b32_e32 v151, v17
	v_writelane_b32 v247, s1, 56
	v_cmp_lt_i32_e64 s[0:1], 8, v3
	v_cndmask_b32_e32 v217, 15, v147, vcc
	s_mov_b32 s86, 0xf149f2ca
	v_writelane_b32 v247, s0, 57
	s_mov_b32 s87, 0xc2c80000
	s_mov_b32 s46, 0x43180000
	v_writelane_b32 v247, s1, 58
	v_cmp_lt_i32_e64 s[0:1], 9, v3
	v_lshlrev_b32_e32 v176, 1, v2
	s_mov_b32 s47, 0x41000000
	v_writelane_b32 v247, s0, 59
	v_bfrev_b32_e32 v50, 1
	v_mov_b32_e32 v218, 0xf149f2ca
	v_writelane_b32 v247, s1, 60
	v_cmp_lt_i32_e64 s[0:1], 10, v3
	v_mov_b32_e32 v219, 0x42c80000
	v_mov_b32_e32 v220, 0x7149f2ca
	v_writelane_b32 v247, s0, 61
	v_mov_b32_e32 v221, 0xc00000
	s_mov_b32 s33, s96
	v_writelane_b32 v247, s1, 62
	v_cmp_lt_i32_e64 s[0:1], 11, v3
	v_sub_u32_e32 v3, v15, v212
	v_cmp_lt_i32_e64 s[90:91], 1, v3
	v_writelane_b32 v247, s0, 63
	v_cmp_lt_i32_e64 s[52:53], 2, v3
	v_cmp_lt_i32_e64 s[54:55], 3, v3
	v_writelane_b32 v246, s1, 0
	v_cmp_lt_i32_e64 s[0:1], 0, v3
	v_cmp_lt_i32_e64 s[56:57], 8, v3
	v_cmp_lt_i32_e64 s[58:59], 9, v3
	v_writelane_b32 v247, s0, 39
	v_cmp_lt_i32_e64 s[60:61], 10, v3
	v_cmp_lt_i32_e64 s[62:63], 11, v3
	v_writelane_b32 v247, s1, 40
	s_mov_b64 s[0:1], 0x1a00c800
	v_lshl_add_u64 v[152:153], v[8:9], 0, s[0:1]
	v_lshl_add_u64 v[8:9], s[20:21], 0, v[16:17]
	v_lshl_add_u64 v[8:9], v[8:9], 0, v[142:143]
	s_mov_b64 s[0:1], 0x1a012800
	v_lshlrev_b32_e32 v16, 1, v11
	v_lshl_add_u64 v[154:155], v[8:9], 0, s[0:1]
	v_lshl_add_u64 v[8:9], s[20:21], 0, v[16:17]
	v_lshlrev_b32_e32 v16, 1, v2
	v_lshl_add_u64 v[8:9], v[8:9], 0, v[16:17]
	s_mov_b64 s[0:1], 0x19ff1b00
	v_lshlrev_b32_e32 v16, 5, v147
	v_lshl_add_u64 v[156:157], v[8:9], 0, s[0:1]
	v_lshl_add_u64 v[8:9], s[20:21], 0, v[16:17]
	v_lshl_add_u64 v[8:9], v[8:9], 0, v[142:143]
	s_mov_b64 s[0:1], 0x1a016800
	v_lshl_add_u64 v[158:159], v[8:9], 0, s[0:1]
	s_add_u32 s0, s20, 0x19ff0800
	s_addc_u32 s1, s21, 0
	s_add_u32 s14, s20, 0x19ff0c00
	s_addc_u32 s15, s21, 0
	v_writelane_b32 v246, s0, 1
	v_cmp_lt_i32_e64 s[64:65], 16, v3
	v_cmp_lt_i32_e64 s[66:67], 17, v3
	v_writelane_b32 v246, s1, 2
	v_lshl_add_u64 v[4:5], s[0:1], 0, v[4:5]
	s_add_u32 s0, s20, 0x1a008800
	s_addc_u32 s1, s21, 0
	s_add_u32 s10, s20, 0x19fe8800
	s_addc_u32 s11, s21, 0
	s_add_u32 s92, s20, 0x4f60000
	v_writelane_b32 v246, s10, 3
	s_addc_u32 s93, s21, 0
	v_lshl_add_u64 v[160:161], v[4:5], 0, v[144:145]
	v_writelane_b32 v246, s11, 4
	s_add_u32 s10, s20, 0x15f60000
	v_writelane_b32 v247, s10, 20
	s_addc_u32 s10, s21, 0
	v_writelane_b32 v247, s10, 21
	s_add_u32 s10, s20, 0x17f60000
	v_writelane_b32 v247, s10, 30
	s_addc_u32 s10, s21, 0
	v_writelane_b32 v247, s10, 31
	s_add_u32 s10, s20, 0x12f60000
	s_addc_u32 s11, s21, 0
	v_writelane_b32 v247, s10, 32
	v_lshl_add_u64 v[4:5], s[14:15], 0, v[6:7]
	v_lshl_add_u64 v[162:163], v[4:5], 0, v[142:143]
	v_writelane_b32 v247, s11, 33
	s_add_u32 s10, s20, 0x10f60000
	v_lshl_add_u64 v[4:5], s[0:1], 0, v[16:17]
	v_writelane_b32 v247, s10, 34
	s_addc_u32 s10, s21, 0
	v_lshl_add_u64 v[164:165], v[4:5], 0, v[142:143]
	v_lshl_add_u64 v[4:5], s[0:1], 0, v[142:143]
	s_add_u32 s0, s20, 0xf60000
	v_writelane_b32 v247, s10, 35
	v_lshl_add_u64 v[166:167], v[4:5], 0, v[16:17]
	s_addc_u32 s1, s21, 0
	v_and_b32_e32 v4, 3, v208
	v_writelane_b32 v247, s0, 37
	v_mul_hi_u32_u24_e32 v5, 0x1800, v12
	v_lshl_or_b32 v4, v4, 4, v150
	v_writelane_b32 v247, s1, 38
	v_lshl_add_u64 v[4:5], s[20:21], 0, v[4:5]
	s_mov_b64 s[0:1], 0x4fc1300
	v_lshl_or_b32 v16, v147, 16, v142
	v_lshl_add_u64 v[168:169], v[4:5], 0, s[0:1]
	v_lshl_add_u64 v[4:5], s[20:21], 0, v[16:17]
	s_mov_b64 s[0:1], 0x17f60080
	v_or_b32_e32 v16, v148, v142
	v_lshl_add_u64 v[170:171], v[4:5], 0, s[0:1]
	v_lshl_add_u64 v[6:7], s[20:21], 0, v[16:17]
	s_mov_b64 s[0:1], 0x15f70000
	v_lshl_add_u64 v[172:173], v[6:7], 0, s[0:1]
	s_mov_b64 s[0:1], 0x10f60100
	v_mad_u32_u24 v143, v147, s8, 0
	s_lshl_b32 s84, s96, 7
	s_lshl_b32 s85, s82, 7
	v_lshl_add_u64 v[174:175], v[4:5], 0, s[0:1]
	v_or_b32_e32 v145, 0x80, v147
	v_cmp_lt_i32_e64 s[68:69], 18, v3
	v_cmp_lt_i32_e64 s[70:71], 19, v3
	v_cmp_lt_i32_e64 s[72:73], 24, v3
	v_cmp_lt_i32_e64 s[74:75], 25, v3
	v_cmp_lt_i32_e64 s[76:77], 26, v3
	v_cmp_lt_i32_e64 s[78:79], 27, v3
	s_branch .LBB0_723
